# stage C final-norm write-out: g_final chunk loads through a ring of free quads, counted vmcnt (no store-ack waits), on top of epi5
# baseline (speedup 1.0000x reference)
.LBB0_808:
	v_add_u32_e32 v16, s15, v176
	ds_read_b64 v[16:17], v16 offset:2560
	s_waitcnt lgkmcnt(0)
	v_mad_u32_u16 v28, v16, v170, v171
	v_mad_u32_u16 v24, v16, v170, v171 op_sel:[1,0,0,0]
	v_mad_u32_u16 v20, v17, v170, v171
	v_mad_u32_u16 v16, v17, v170, v171 op_sel:[1,0,0,0]
	global_load_dwordx4 v[28:31], v28, s[34:35]
	global_load_dwordx4 v[24:27], v24, s[34:35]
	global_load_dwordx4 v[20:23], v20, s[34:35]
	global_load_dwordx4 v[16:19], v16, s[34:35]
	v_add_u32_e32 v113, s17, v176
	ds_read_b128 v[114:117], v113
	s_waitcnt vmcnt(7)
	v_cvt_scalef32_pk_f32_fp4 v[118:119], v12, 1.0
	s_waitcnt lgkmcnt(0)
	v_pk_fma_f32 v[80:81], v[118:119], v[114:115], v[80:81] op_sel_hi:[1,0,1]
	v_cvt_scalef32_pk_f32_fp4 v[118:119], v12, 1.0 op_sel:[1,0,0]
	v_pk_fma_f32 v[82:83], v[118:119], v[114:115], v[82:83] op_sel_hi:[1,0,1]
	v_cvt_scalef32_pk_f32_fp4 v[118:119], v12, 1.0 op_sel:[0,1,0]
	v_pk_fma_f32 v[84:85], v[118:119], v[114:115], v[84:85] op_sel_hi:[1,0,1]
	v_cvt_scalef32_pk_f32_fp4 v[118:119], v12, 1.0 op_sel:[1,1,0]
	v_pk_fma_f32 v[86:87], v[118:119], v[114:115], v[86:87] op_sel_hi:[1,0,1]
	v_cvt_scalef32_pk_f32_fp4 v[118:119], v13, 1.0
	v_pk_fma_f32 v[88:89], v[118:119], v[114:115], v[88:89] op_sel_hi:[1,0,1]
	v_cvt_scalef32_pk_f32_fp4 v[118:119], v13, 1.0 op_sel:[1,0,0]
	v_pk_fma_f32 v[90:91], v[118:119], v[114:115], v[90:91] op_sel_hi:[1,0,1]
	v_cvt_scalef32_pk_f32_fp4 v[118:119], v13, 1.0 op_sel:[0,1,0]
	v_cvt_scalef32_pk_f32_fp4 v[12:13], v13, 1.0 op_sel:[1,1,0]
	v_pk_fma_f32 v[12:13], v[12:13], v[114:115], v[94:95] op_sel_hi:[1,0,1]
	v_cvt_scalef32_pk_f32_fp4 v[94:95], v14, 1.0
	v_pk_fma_f32 v[94:95], v[94:95], v[114:115], v[96:97] op_sel_hi:[1,0,1]
	v_cvt_scalef32_pk_f32_fp4 v[96:97], v14, 1.0 op_sel:[1,0,0]
	v_pk_fma_f32 v[96:97], v[96:97], v[114:115], v[98:99] op_sel_hi:[1,0,1]
	v_cvt_scalef32_pk_f32_fp4 v[98:99], v14, 1.0 op_sel:[0,1,0]
	v_pk_fma_f32 v[98:99], v[98:99], v[114:115], v[100:101] op_sel_hi:[1,0,1]
	v_cvt_scalef32_pk_f32_fp4 v[100:101], v14, 1.0 op_sel:[1,1,0]
	v_pk_fma_f32 v[100:101], v[100:101], v[114:115], v[102:103] op_sel_hi:[1,0,1]
	v_cvt_scalef32_pk_f32_fp4 v[102:103], v15, 1.0
	v_pk_fma_f32 v[102:103], v[102:103], v[114:115], v[104:105] op_sel_hi:[1,0,1]
	v_cvt_scalef32_pk_f32_fp4 v[104:105], v15, 1.0 op_sel:[1,0,0]
	v_pk_fma_f32 v[104:105], v[104:105], v[114:115], v[106:107] op_sel_hi:[1,0,1]
	v_cvt_scalef32_pk_f32_fp4 v[106:107], v15, 1.0 op_sel:[0,1,0]
	v_pk_fma_f32 v[106:107], v[106:107], v[114:115], v[108:109] op_sel_hi:[1,0,1]
	s_waitcnt vmcnt(6)
	v_cvt_scalef32_pk_f32_fp4 v[108:109], v8, 1.0
	v_pk_fma_f32 v[80:81], v[108:109], v[114:115], v[80:81] op_sel:[0,1,0]
	v_cvt_scalef32_pk_f32_fp4 v[108:109], v8, 1.0 op_sel:[1,0,0]
	v_pk_fma_f32 v[82:83], v[108:109], v[114:115], v[82:83] op_sel:[0,1,0]
	v_cvt_scalef32_pk_f32_fp4 v[108:109], v8, 1.0 op_sel:[0,1,0]
	v_pk_fma_f32 v[84:85], v[108:109], v[114:115], v[84:85] op_sel:[0,1,0]
	v_cvt_scalef32_pk_f32_fp4 v[108:109], v8, 1.0 op_sel:[1,1,0]
	v_pk_fma_f32 v[86:87], v[108:109], v[114:115], v[86:87] op_sel:[0,1,0]
	v_cvt_scalef32_pk_f32_fp4 v[108:109], v9, 1.0
	v_pk_fma_f32 v[88:89], v[108:109], v[114:115], v[88:89] op_sel:[0,1,0]
	v_cvt_scalef32_pk_f32_fp4 v[108:109], v9, 1.0 op_sel:[1,0,0]
	v_pk_fma_f32 v[90:91], v[108:109], v[114:115], v[90:91] op_sel:[0,1,0]
	v_cvt_scalef32_pk_f32_fp4 v[108:109], v9, 1.0 op_sel:[0,1,0]
	v_cvt_scalef32_pk_f32_fp4 v[8:9], v9, 1.0 op_sel:[1,1,0]
	v_pk_fma_f32 v[8:9], v[8:9], v[114:115], v[12:13] op_sel:[0,1,0]
	v_cvt_scalef32_pk_f32_fp4 v[12:13], v10, 1.0
	v_pk_fma_f32 v[12:13], v[12:13], v[114:115], v[94:95] op_sel:[0,1,0]
	v_cvt_scalef32_pk_f32_fp4 v[94:95], v10, 1.0 op_sel:[1,0,0]
	v_pk_fma_f32 v[94:95], v[94:95], v[114:115], v[96:97] op_sel:[0,1,0]
	v_cvt_scalef32_pk_f32_fp4 v[96:97], v10, 1.0 op_sel:[0,1,0]
	v_pk_fma_f32 v[96:97], v[96:97], v[114:115], v[98:99] op_sel:[0,1,0]
	v_cvt_scalef32_pk_f32_fp4 v[98:99], v10, 1.0 op_sel:[1,1,0]
	v_pk_fma_f32 v[98:99], v[98:99], v[114:115], v[100:101] op_sel:[0,1,0]
	v_cvt_scalef32_pk_f32_fp4 v[100:101], v11, 1.0
	v_cvt_scalef32_pk_f32_fp4 v[14:15], v15, 1.0 op_sel:[1,1,0]
	v_pk_fma_f32 v[100:101], v[100:101], v[114:115], v[102:103] op_sel:[0,1,0]
	v_cvt_scalef32_pk_f32_fp4 v[102:103], v11, 1.0 op_sel:[1,0,0]
	v_pk_fma_f32 v[14:15], v[14:15], v[114:115], v[110:111] op_sel_hi:[1,0,1]
	v_pk_fma_f32 v[102:103], v[102:103], v[114:115], v[104:105] op_sel:[0,1,0]
	v_cvt_scalef32_pk_f32_fp4 v[104:105], v11, 1.0 op_sel:[0,1,0]
	v_cvt_scalef32_pk_f32_fp4 v[10:11], v11, 1.0 op_sel:[1,1,0]
	v_pk_fma_f32 v[10:11], v[10:11], v[114:115], v[14:15] op_sel:[0,1,0]
	s_waitcnt vmcnt(5)
	v_cvt_scalef32_pk_f32_fp4 v[14:15], v4, 1.0
	v_pk_fma_f32 v[14:15], v[14:15], v[116:117], v[80:81] op_sel_hi:[1,0,1]
	v_cvt_scalef32_pk_f32_fp4 v[80:81], v4, 1.0 op_sel:[1,0,0]
	v_pk_fma_f32 v[82:83], v[80:81], v[116:117], v[82:83] op_sel_hi:[1,0,1]
	v_cvt_scalef32_pk_f32_fp4 v[80:81], v4, 1.0 op_sel:[0,1,0]
	v_pk_fma_f32 v[84:85], v[80:81], v[116:117], v[84:85] op_sel_hi:[1,0,1]
	v_cvt_scalef32_pk_f32_fp4 v[80:81], v4, 1.0 op_sel:[1,1,0]
	v_pk_fma_f32 v[86:87], v[80:81], v[116:117], v[86:87] op_sel_hi:[1,0,1]
	v_cvt_scalef32_pk_f32_fp4 v[80:81], v5, 1.0
	v_pk_fma_f32 v[88:89], v[80:81], v[116:117], v[88:89] op_sel_hi:[1,0,1]
	v_cvt_scalef32_pk_f32_fp4 v[80:81], v5, 1.0 op_sel:[1,0,0]
	v_pk_fma_f32 v[90:91], v[80:81], v[116:117], v[90:91] op_sel_hi:[1,0,1]
	v_cvt_scalef32_pk_f32_fp4 v[80:81], v5, 1.0 op_sel:[0,1,0]
	v_cvt_scalef32_pk_f32_fp4 v[4:5], v5, 1.0 op_sel:[1,1,0]
	v_pk_fma_f32 v[8:9], v[4:5], v[116:117], v[8:9] op_sel_hi:[1,0,1]
	v_cvt_scalef32_pk_f32_fp4 v[4:5], v6, 1.0
	v_pk_fma_f32 v[12:13], v[4:5], v[116:117], v[12:13] op_sel_hi:[1,0,1]
	v_cvt_scalef32_pk_f32_fp4 v[4:5], v6, 1.0 op_sel:[1,0,0]
	v_pk_fma_f32 v[92:93], v[118:119], v[114:115], v[92:93] op_sel_hi:[1,0,1]
	v_pk_fma_f32 v[104:105], v[104:105], v[114:115], v[106:107] op_sel:[0,1,0]
	v_pk_fma_f32 v[106:107], v[4:5], v[116:117], v[94:95] op_sel_hi:[1,0,1]
	v_cvt_scalef32_pk_f32_fp4 v[4:5], v6, 1.0 op_sel:[0,1,0]
	v_pk_fma_f32 v[92:93], v[108:109], v[114:115], v[92:93] op_sel:[0,1,0]
	v_pk_fma_f32 v[108:109], v[4:5], v[116:117], v[96:97] op_sel_hi:[1,0,1]
	v_cvt_scalef32_pk_f32_fp4 v[4:5], v6, 1.0 op_sel:[1,1,0]
	v_pk_fma_f32 v[110:111], v[4:5], v[116:117], v[98:99] op_sel_hi:[1,0,1]
	v_cvt_scalef32_pk_f32_fp4 v[4:5], v7, 1.0
	v_pk_fma_f32 v[114:115], v[4:5], v[116:117], v[100:101] op_sel_hi:[1,0,1]
	v_cvt_scalef32_pk_f32_fp4 v[4:5], v7, 1.0 op_sel:[1,0,0]
	v_pk_fma_f32 v[118:119], v[4:5], v[116:117], v[102:103] op_sel_hi:[1,0,1]
	v_cvt_scalef32_pk_f32_fp4 v[4:5], v7, 1.0 op_sel:[0,1,0]
	v_pk_fma_f32 v[120:121], v[4:5], v[116:117], v[104:105] op_sel_hi:[1,0,1]
	v_cvt_scalef32_pk_f32_fp4 v[4:5], v7, 1.0 op_sel:[1,1,0]
	v_pk_fma_f32 v[4:5], v[4:5], v[116:117], v[10:11] op_sel_hi:[1,0,1]
	v_mov_b32_e32 v6, v117
	s_waitcnt vmcnt(4)
	v_cvt_scalef32_pk_f32_fp4 v[10:11], v0, 1.0
	v_pk_fma_f32 v[92:93], v[80:81], v[116:117], v[92:93] op_sel_hi:[1,0,1]
	v_pk_fma_f32 v[80:81], v[10:11], v[6:7], v[14:15] op_sel_hi:[1,0,1]
	v_cvt_scalef32_pk_f32_fp4 v[10:11], v0, 1.0 op_sel:[1,0,0]
	v_pk_fma_f32 v[82:83], v[10:11], v[6:7], v[82:83] op_sel_hi:[1,0,1]
	v_cvt_scalef32_pk_f32_fp4 v[10:11], v0, 1.0 op_sel:[0,1,0]
	v_pk_fma_f32 v[84:85], v[10:11], v[6:7], v[84:85] op_sel_hi:[1,0,1]
	v_cvt_scalef32_pk_f32_fp4 v[10:11], v0, 1.0 op_sel:[1,1,0]
	v_pk_fma_f32 v[86:87], v[10:11], v[6:7], v[86:87] op_sel_hi:[1,0,1]
	v_cvt_scalef32_pk_f32_fp4 v[10:11], v1, 1.0
	v_pk_fma_f32 v[88:89], v[10:11], v[6:7], v[88:89] op_sel_hi:[1,0,1]
	v_cvt_scalef32_pk_f32_fp4 v[10:11], v1, 1.0 op_sel:[1,0,0]
	v_pk_fma_f32 v[90:91], v[10:11], v[6:7], v[90:91] op_sel_hi:[1,0,1]
	v_cvt_scalef32_pk_f32_fp4 v[10:11], v1, 1.0 op_sel:[0,1,0]
	v_cvt_scalef32_pk_f32_fp4 v[0:1], v1, 1.0 op_sel:[1,1,0]
	v_pk_fma_f32 v[94:95], v[0:1], v[6:7], v[8:9] op_sel_hi:[1,0,1]
	v_cvt_scalef32_pk_f32_fp4 v[0:1], v2, 1.0
	v_pk_fma_f32 v[96:97], v[0:1], v[6:7], v[12:13] op_sel_hi:[1,0,1]
	v_cvt_scalef32_pk_f32_fp4 v[0:1], v2, 1.0 op_sel:[1,0,0]
	v_pk_fma_f32 v[98:99], v[0:1], v[6:7], v[106:107] op_sel_hi:[1,0,1]
	v_cvt_scalef32_pk_f32_fp4 v[0:1], v2, 1.0 op_sel:[0,1,0]
	v_pk_fma_f32 v[100:101], v[0:1], v[6:7], v[108:109] op_sel_hi:[1,0,1]
	v_cvt_scalef32_pk_f32_fp4 v[0:1], v2, 1.0 op_sel:[1,1,0]
	v_pk_fma_f32 v[102:103], v[0:1], v[6:7], v[110:111] op_sel_hi:[1,0,1]
	v_cvt_scalef32_pk_f32_fp4 v[0:1], v3, 1.0
	v_pk_fma_f32 v[104:105], v[0:1], v[6:7], v[114:115] op_sel_hi:[1,0,1]
	v_cvt_scalef32_pk_f32_fp4 v[0:1], v3, 1.0 op_sel:[1,0,0]
	v_pk_fma_f32 v[106:107], v[0:1], v[6:7], v[118:119] op_sel_hi:[1,0,1]
	v_cvt_scalef32_pk_f32_fp4 v[0:1], v3, 1.0 op_sel:[0,1,0]
	v_pk_fma_f32 v[108:109], v[0:1], v[6:7], v[120:121] op_sel_hi:[1,0,1]
	v_cvt_scalef32_pk_f32_fp4 v[0:1], v3, 1.0 op_sel:[1,1,0]
	v_pk_fma_f32 v[92:93], v[10:11], v[6:7], v[92:93] op_sel_hi:[1,0,1]
	v_pk_fma_f32 v[110:111], v[0:1], v[6:7], v[4:5] op_sel_hi:[1,0,1]
	v_add_u32_e32 v0, s18, v176
	ds_read_b64 v[0:1], v0
	s_waitcnt lgkmcnt(0)
	v_mad_u32_u16 v12, v0, v170, v171
	v_mad_u32_u16 v8, v0, v170, v171 op_sel:[1,0,0,0]
	v_mad_u32_u16 v4, v1, v170, v171
	v_mad_u32_u16 v0, v1, v170, v171 op_sel:[1,0,0,0]
	global_load_dwordx4 v[12:15], v12, s[34:35]
	global_load_dwordx4 v[8:11], v8, s[34:35]
	global_load_dwordx4 v[4:7], v4, s[34:35]
	global_load_dwordx4 v[0:3], v0, s[34:35]
	v_add_u32_e32 v113, s14, v176
	ds_read_b128 v[114:117], v113
	s_waitcnt vmcnt(7)
	v_cvt_scalef32_pk_f32_fp4 v[118:119], v28, 1.0
	s_waitcnt lgkmcnt(0)
	v_pk_fma_f32 v[48:49], v[118:119], v[114:115], v[48:49] op_sel_hi:[1,0,1]
	v_cvt_scalef32_pk_f32_fp4 v[118:119], v28, 1.0 op_sel:[1,0,0]
	v_pk_fma_f32 v[50:51], v[118:119], v[114:115], v[50:51] op_sel_hi:[1,0,1]
	v_cvt_scalef32_pk_f32_fp4 v[118:119], v28, 1.0 op_sel:[0,1,0]
	v_pk_fma_f32 v[52:53], v[118:119], v[114:115], v[52:53] op_sel_hi:[1,0,1]
	v_cvt_scalef32_pk_f32_fp4 v[118:119], v28, 1.0 op_sel:[1,1,0]
	v_pk_fma_f32 v[54:55], v[118:119], v[114:115], v[54:55] op_sel_hi:[1,0,1]
	v_cvt_scalef32_pk_f32_fp4 v[118:119], v29, 1.0
	v_pk_fma_f32 v[56:57], v[118:119], v[114:115], v[56:57] op_sel_hi:[1,0,1]
	v_cvt_scalef32_pk_f32_fp4 v[118:119], v29, 1.0 op_sel:[1,0,0]
	v_pk_fma_f32 v[58:59], v[118:119], v[114:115], v[58:59] op_sel_hi:[1,0,1]
	v_cvt_scalef32_pk_f32_fp4 v[118:119], v29, 1.0 op_sel:[0,1,0]
	v_cvt_scalef32_pk_f32_fp4 v[28:29], v29, 1.0 op_sel:[1,1,0]
	v_pk_fma_f32 v[28:29], v[28:29], v[114:115], v[62:63] op_sel_hi:[1,0,1]
	v_cvt_scalef32_pk_f32_fp4 v[62:63], v30, 1.0
	v_pk_fma_f32 v[62:63], v[62:63], v[114:115], v[64:65] op_sel_hi:[1,0,1]
	v_cvt_scalef32_pk_f32_fp4 v[64:65], v30, 1.0 op_sel:[1,0,0]
	v_pk_fma_f32 v[64:65], v[64:65], v[114:115], v[66:67] op_sel_hi:[1,0,1]
	v_cvt_scalef32_pk_f32_fp4 v[66:67], v30, 1.0 op_sel:[0,1,0]
	v_pk_fma_f32 v[66:67], v[66:67], v[114:115], v[68:69] op_sel_hi:[1,0,1]
	v_cvt_scalef32_pk_f32_fp4 v[68:69], v30, 1.0 op_sel:[1,1,0]
	v_pk_fma_f32 v[68:69], v[68:69], v[114:115], v[70:71] op_sel_hi:[1,0,1]
	v_cvt_scalef32_pk_f32_fp4 v[70:71], v31, 1.0
	v_pk_fma_f32 v[70:71], v[70:71], v[114:115], v[72:73] op_sel_hi:[1,0,1]
	v_cvt_scalef32_pk_f32_fp4 v[72:73], v31, 1.0 op_sel:[1,0,0]
	v_pk_fma_f32 v[72:73], v[72:73], v[114:115], v[74:75] op_sel_hi:[1,0,1]
	v_cvt_scalef32_pk_f32_fp4 v[74:75], v31, 1.0 op_sel:[0,1,0]
	v_pk_fma_f32 v[74:75], v[74:75], v[114:115], v[76:77] op_sel_hi:[1,0,1]
	s_waitcnt vmcnt(6)
	v_cvt_scalef32_pk_f32_fp4 v[76:77], v24, 1.0
	v_pk_fma_f32 v[48:49], v[76:77], v[114:115], v[48:49] op_sel:[0,1,0]
	v_cvt_scalef32_pk_f32_fp4 v[76:77], v24, 1.0 op_sel:[1,0,0]
	v_pk_fma_f32 v[50:51], v[76:77], v[114:115], v[50:51] op_sel:[0,1,0]
	v_cvt_scalef32_pk_f32_fp4 v[76:77], v24, 1.0 op_sel:[0,1,0]
	v_pk_fma_f32 v[52:53], v[76:77], v[114:115], v[52:53] op_sel:[0,1,0]
	v_cvt_scalef32_pk_f32_fp4 v[76:77], v24, 1.0 op_sel:[1,1,0]
	v_pk_fma_f32 v[54:55], v[76:77], v[114:115], v[54:55] op_sel:[0,1,0]
	v_cvt_scalef32_pk_f32_fp4 v[76:77], v25, 1.0
	v_pk_fma_f32 v[56:57], v[76:77], v[114:115], v[56:57] op_sel:[0,1,0]
	v_cvt_scalef32_pk_f32_fp4 v[76:77], v25, 1.0 op_sel:[1,0,0]
	v_pk_fma_f32 v[58:59], v[76:77], v[114:115], v[58:59] op_sel:[0,1,0]
	v_cvt_scalef32_pk_f32_fp4 v[76:77], v25, 1.0 op_sel:[0,1,0]
	v_cvt_scalef32_pk_f32_fp4 v[24:25], v25, 1.0 op_sel:[1,1,0]
	v_pk_fma_f32 v[24:25], v[24:25], v[114:115], v[28:29] op_sel:[0,1,0]
	v_cvt_scalef32_pk_f32_fp4 v[28:29], v26, 1.0
	v_pk_fma_f32 v[28:29], v[28:29], v[114:115], v[62:63] op_sel:[0,1,0]
	v_cvt_scalef32_pk_f32_fp4 v[62:63], v26, 1.0 op_sel:[1,0,0]
	v_pk_fma_f32 v[62:63], v[62:63], v[114:115], v[64:65] op_sel:[0,1,0]
	v_cvt_scalef32_pk_f32_fp4 v[64:65], v26, 1.0 op_sel:[0,1,0]
	v_pk_fma_f32 v[64:65], v[64:65], v[114:115], v[66:67] op_sel:[0,1,0]
	v_cvt_scalef32_pk_f32_fp4 v[66:67], v26, 1.0 op_sel:[1,1,0]
	v_pk_fma_f32 v[66:67], v[66:67], v[114:115], v[68:69] op_sel:[0,1,0]
	v_cvt_scalef32_pk_f32_fp4 v[68:69], v27, 1.0
	v_cvt_scalef32_pk_f32_fp4 v[30:31], v31, 1.0 op_sel:[1,1,0]
	v_pk_fma_f32 v[68:69], v[68:69], v[114:115], v[70:71] op_sel:[0,1,0]
	v_cvt_scalef32_pk_f32_fp4 v[70:71], v27, 1.0 op_sel:[1,0,0]
	v_pk_fma_f32 v[30:31], v[30:31], v[114:115], v[78:79] op_sel_hi:[1,0,1]
	v_pk_fma_f32 v[70:71], v[70:71], v[114:115], v[72:73] op_sel:[0,1,0]
	v_cvt_scalef32_pk_f32_fp4 v[72:73], v27, 1.0 op_sel:[0,1,0]
	v_cvt_scalef32_pk_f32_fp4 v[26:27], v27, 1.0 op_sel:[1,1,0]
	v_pk_fma_f32 v[26:27], v[26:27], v[114:115], v[30:31] op_sel:[0,1,0]
	s_waitcnt vmcnt(5)
	v_cvt_scalef32_pk_f32_fp4 v[30:31], v20, 1.0
	v_pk_fma_f32 v[30:31], v[30:31], v[116:117], v[48:49] op_sel_hi:[1,0,1]
	v_cvt_scalef32_pk_f32_fp4 v[48:49], v20, 1.0 op_sel:[1,0,0]
	v_pk_fma_f32 v[50:51], v[48:49], v[116:117], v[50:51] op_sel_hi:[1,0,1]
	v_cvt_scalef32_pk_f32_fp4 v[48:49], v20, 1.0 op_sel:[0,1,0]
	v_pk_fma_f32 v[52:53], v[48:49], v[116:117], v[52:53] op_sel_hi:[1,0,1]
	v_cvt_scalef32_pk_f32_fp4 v[48:49], v20, 1.0 op_sel:[1,1,0]
	v_pk_fma_f32 v[54:55], v[48:49], v[116:117], v[54:55] op_sel_hi:[1,0,1]
	v_cvt_scalef32_pk_f32_fp4 v[48:49], v21, 1.0
	v_pk_fma_f32 v[56:57], v[48:49], v[116:117], v[56:57] op_sel_hi:[1,0,1]
	v_cvt_scalef32_pk_f32_fp4 v[48:49], v21, 1.0 op_sel:[1,0,0]
	v_pk_fma_f32 v[58:59], v[48:49], v[116:117], v[58:59] op_sel_hi:[1,0,1]
	v_cvt_scalef32_pk_f32_fp4 v[48:49], v21, 1.0 op_sel:[0,1,0]
	v_cvt_scalef32_pk_f32_fp4 v[20:21], v21, 1.0 op_sel:[1,1,0]
	v_pk_fma_f32 v[24:25], v[20:21], v[116:117], v[24:25] op_sel_hi:[1,0,1]
	v_cvt_scalef32_pk_f32_fp4 v[20:21], v22, 1.0
	v_pk_fma_f32 v[28:29], v[20:21], v[116:117], v[28:29] op_sel_hi:[1,0,1]
	v_cvt_scalef32_pk_f32_fp4 v[20:21], v22, 1.0 op_sel:[1,0,0]
	v_pk_fma_f32 v[60:61], v[118:119], v[114:115], v[60:61] op_sel_hi:[1,0,1]
	v_pk_fma_f32 v[72:73], v[72:73], v[114:115], v[74:75] op_sel:[0,1,0]
	v_pk_fma_f32 v[74:75], v[20:21], v[116:117], v[62:63] op_sel_hi:[1,0,1]
	v_cvt_scalef32_pk_f32_fp4 v[20:21], v22, 1.0 op_sel:[0,1,0]
	v_pk_fma_f32 v[60:61], v[76:77], v[114:115], v[60:61] op_sel:[0,1,0]
	v_pk_fma_f32 v[76:77], v[20:21], v[116:117], v[64:65] op_sel_hi:[1,0,1]
	v_cvt_scalef32_pk_f32_fp4 v[20:21], v22, 1.0 op_sel:[1,1,0]
	v_pk_fma_f32 v[78:79], v[20:21], v[116:117], v[66:67] op_sel_hi:[1,0,1]
	v_cvt_scalef32_pk_f32_fp4 v[20:21], v23, 1.0
	v_pk_fma_f32 v[114:115], v[20:21], v[116:117], v[68:69] op_sel_hi:[1,0,1]
	v_cvt_scalef32_pk_f32_fp4 v[20:21], v23, 1.0 op_sel:[1,0,0]
	v_pk_fma_f32 v[118:119], v[20:21], v[116:117], v[70:71] op_sel_hi:[1,0,1]
	v_cvt_scalef32_pk_f32_fp4 v[20:21], v23, 1.0 op_sel:[0,1,0]
	v_pk_fma_f32 v[120:121], v[20:21], v[116:117], v[72:73] op_sel_hi:[1,0,1]
	v_cvt_scalef32_pk_f32_fp4 v[20:21], v23, 1.0 op_sel:[1,1,0]
	v_pk_fma_f32 v[20:21], v[20:21], v[116:117], v[26:27] op_sel_hi:[1,0,1]
	v_mov_b32_e32 v22, v117
	s_waitcnt vmcnt(4)
	v_cvt_scalef32_pk_f32_fp4 v[26:27], v16, 1.0
	v_pk_fma_f32 v[60:61], v[48:49], v[116:117], v[60:61] op_sel_hi:[1,0,1]
	v_pk_fma_f32 v[48:49], v[26:27], v[22:23], v[30:31] op_sel_hi:[1,0,1]
	v_cvt_scalef32_pk_f32_fp4 v[26:27], v16, 1.0 op_sel:[1,0,0]
	v_pk_fma_f32 v[50:51], v[26:27], v[22:23], v[50:51] op_sel_hi:[1,0,1]
	v_cvt_scalef32_pk_f32_fp4 v[26:27], v16, 1.0 op_sel:[0,1,0]
	v_pk_fma_f32 v[52:53], v[26:27], v[22:23], v[52:53] op_sel_hi:[1,0,1]
	v_cvt_scalef32_pk_f32_fp4 v[26:27], v16, 1.0 op_sel:[1,1,0]
	v_pk_fma_f32 v[54:55], v[26:27], v[22:23], v[54:55] op_sel_hi:[1,0,1]
	v_cvt_scalef32_pk_f32_fp4 v[26:27], v17, 1.0
	v_pk_fma_f32 v[56:57], v[26:27], v[22:23], v[56:57] op_sel_hi:[1,0,1]
	v_cvt_scalef32_pk_f32_fp4 v[26:27], v17, 1.0 op_sel:[1,0,0]
	v_pk_fma_f32 v[58:59], v[26:27], v[22:23], v[58:59] op_sel_hi:[1,0,1]
	v_cvt_scalef32_pk_f32_fp4 v[26:27], v17, 1.0 op_sel:[0,1,0]
	v_cvt_scalef32_pk_f32_fp4 v[16:17], v17, 1.0 op_sel:[1,1,0]
	v_pk_fma_f32 v[62:63], v[16:17], v[22:23], v[24:25] op_sel_hi:[1,0,1]
	v_cvt_scalef32_pk_f32_fp4 v[16:17], v18, 1.0
	v_pk_fma_f32 v[64:65], v[16:17], v[22:23], v[28:29] op_sel_hi:[1,0,1]
	v_cvt_scalef32_pk_f32_fp4 v[16:17], v18, 1.0 op_sel:[1,0,0]
	v_pk_fma_f32 v[66:67], v[16:17], v[22:23], v[74:75] op_sel_hi:[1,0,1]
	v_cvt_scalef32_pk_f32_fp4 v[16:17], v18, 1.0 op_sel:[0,1,0]
	v_pk_fma_f32 v[68:69], v[16:17], v[22:23], v[76:77] op_sel_hi:[1,0,1]
	v_cvt_scalef32_pk_f32_fp4 v[16:17], v18, 1.0 op_sel:[1,1,0]
	v_pk_fma_f32 v[70:71], v[16:17], v[22:23], v[78:79] op_sel_hi:[1,0,1]
	v_cvt_scalef32_pk_f32_fp4 v[16:17], v19, 1.0
	v_pk_fma_f32 v[72:73], v[16:17], v[22:23], v[114:115] op_sel_hi:[1,0,1]
	v_cvt_scalef32_pk_f32_fp4 v[16:17], v19, 1.0 op_sel:[1,0,0]
	v_pk_fma_f32 v[74:75], v[16:17], v[22:23], v[118:119] op_sel_hi:[1,0,1]
	v_cvt_scalef32_pk_f32_fp4 v[16:17], v19, 1.0 op_sel:[0,1,0]
	v_pk_fma_f32 v[76:77], v[16:17], v[22:23], v[120:121] op_sel_hi:[1,0,1]
	v_cvt_scalef32_pk_f32_fp4 v[16:17], v19, 1.0 op_sel:[1,1,0]
	v_pk_fma_f32 v[60:61], v[26:27], v[22:23], v[60:61] op_sel_hi:[1,0,1]
	v_pk_fma_f32 v[78:79], v[16:17], v[22:23], v[20:21] op_sel_hi:[1,0,1]
	s_add_i32 s18, s18, 8
	s_add_i32 s16, s16, -1
	s_add_i32 s17, s17, 16
	s_add_i32 s14, s14, 16
	s_add_i32 s15, s15, 8
	s_cmp_lg_u32 s16, 0
	s_cbranch_scc1 .LBB0_808
	v_lshl_add_u32 v119, s13, 8, v177
	ds_read_b64 v[24:25], v119 offset:2808
	v_mov_b32_e32 v17, v137
	s_waitcnt lgkmcnt(0)
	v_lshlrev_b32_sdwa v136, v188, v24 dst_sel:DWORD dst_unused:UNUSED_PAD src0_sel:DWORD src1_sel:WORD_0
	v_lshlrev_b32_sdwa v16, v188, v24 dst_sel:DWORD dst_unused:UNUSED_PAD src0_sel:DWORD src1_sel:WORD_1
	v_lshl_add_u64 v[18:19], v[32:33], 0, v[136:137]
	v_lshlrev_b32_sdwa v24, v188, v25 dst_sel:DWORD dst_unused:UNUSED_PAD src0_sel:DWORD src1_sel:WORD_1
	v_lshlrev_b32_sdwa v136, v188, v25 dst_sel:DWORD dst_unused:UNUSED_PAD src0_sel:DWORD src1_sel:WORD_0
	v_mov_b32_e32 v25, v137
	v_lshl_add_u64 v[20:21], v[32:33], 0, v[16:17]
	v_lshl_add_u64 v[26:27], v[32:33], 0, v[136:137]
	v_lshl_add_u64 v[28:29], v[32:33], 0, v[24:25]
	global_load_dwordx4 v[16:19], v[18:19], off
	s_nop 0
	global_load_dwordx4 v[20:23], v[20:21], off
	s_nop 0
	global_load_dwordx4 v[24:27], v[26:27], off
	s_nop 0
	global_load_dwordx4 v[28:31], v[28:29], off
	v_lshl_add_u32 v112, s8, 8, v112
	ds_read_b128 v[112:115], v112 offset:5104
	s_waitcnt vmcnt(7)
	v_cvt_scalef32_pk_f32_fp4 v[124:125], v15, 1.0 op_sel:[1,1,0]
	s_waitcnt vmcnt(6)
	v_cvt_scalef32_pk_f32_fp4 v[122:123], v11, 1.0 op_sel:[1,1,0]
	s_waitcnt lgkmcnt(0)
	v_pk_fma_f32 v[110:111], v[124:125], v[112:113], v[110:111] op_sel_hi:[1,0,1]
	v_cvt_scalef32_pk_f32_fp4 v[124:125], v15, 1.0 op_sel:[0,1,0]
	s_waitcnt vmcnt(5)
	v_cvt_scalef32_pk_f32_fp4 v[120:121], v7, 1.0 op_sel:[1,1,0]
	v_pk_fma_f32 v[110:111], v[122:123], v[112:113], v[110:111] op_sel:[0,1,0]
	v_cvt_scalef32_pk_f32_fp4 v[122:123], v11, 1.0 op_sel:[0,1,0]
	v_pk_fma_f32 v[108:109], v[124:125], v[112:113], v[108:109] op_sel_hi:[1,0,1]
	v_cvt_scalef32_pk_f32_fp4 v[124:125], v15, 1.0 op_sel:[1,0,0]
	s_waitcnt vmcnt(4)
	v_cvt_scalef32_pk_f32_fp4 v[116:117], v3, 1.0 op_sel:[1,1,0]
	v_mov_b32_e32 v118, v115
	v_pk_fma_f32 v[110:111], v[120:121], v[114:115], v[110:111] op_sel_hi:[1,0,1]
	v_cvt_scalef32_pk_f32_fp4 v[120:121], v7, 1.0 op_sel:[0,1,0]
	v_pk_fma_f32 v[108:109], v[122:123], v[112:113], v[108:109] op_sel:[0,1,0]
	v_cvt_scalef32_pk_f32_fp4 v[122:123], v11, 1.0 op_sel:[1,0,0]
	v_pk_fma_f32 v[106:107], v[124:125], v[112:113], v[106:107] op_sel_hi:[1,0,1]
	v_cvt_scalef32_pk_f32_fp4 v[124:125], v15, 1.0
	v_pk_fma_f32 v[110:111], v[116:117], v[118:119], v[110:111] op_sel_hi:[1,0,1]
	v_cvt_scalef32_pk_f32_fp4 v[116:117], v3, 1.0 op_sel:[0,1,0]
	v_pk_fma_f32 v[108:109], v[120:121], v[114:115], v[108:109] op_sel_hi:[1,0,1]
	v_cvt_scalef32_pk_f32_fp4 v[120:121], v7, 1.0 op_sel:[1,0,0]
	v_pk_fma_f32 v[106:107], v[122:123], v[112:113], v[106:107] op_sel:[0,1,0]
	v_cvt_scalef32_pk_f32_fp4 v[122:123], v11, 1.0
	v_pk_fma_f32 v[104:105], v[124:125], v[112:113], v[104:105] op_sel_hi:[1,0,1]
	v_cvt_scalef32_pk_f32_fp4 v[124:125], v14, 1.0 op_sel:[1,1,0]
	v_pk_fma_f32 v[108:109], v[116:117], v[118:119], v[108:109] op_sel_hi:[1,0,1]
	v_cvt_scalef32_pk_f32_fp4 v[116:117], v3, 1.0 op_sel:[1,0,0]
	v_pk_fma_f32 v[106:107], v[120:121], v[114:115], v[106:107] op_sel_hi:[1,0,1]
	v_cvt_scalef32_pk_f32_fp4 v[120:121], v7, 1.0
	v_pk_fma_f32 v[104:105], v[122:123], v[112:113], v[104:105] op_sel:[0,1,0]
	v_cvt_scalef32_pk_f32_fp4 v[122:123], v10, 1.0 op_sel:[1,1,0]
	v_pk_fma_f32 v[102:103], v[124:125], v[112:113], v[102:103] op_sel_hi:[1,0,1]
	v_pk_fma_f32 v[106:107], v[116:117], v[118:119], v[106:107] op_sel_hi:[1,0,1]
	v_cvt_scalef32_pk_f32_fp4 v[116:117], v3, 1.0
	v_pk_fma_f32 v[104:105], v[120:121], v[114:115], v[104:105] op_sel_hi:[1,0,1]
	v_cvt_scalef32_pk_f32_fp4 v[120:121], v6, 1.0 op_sel:[1,1,0]
	v_pk_fma_f32 v[102:103], v[122:123], v[112:113], v[102:103] op_sel:[0,1,0]
	v_cvt_scalef32_pk_f32_fp4 v[122:123], v14, 1.0 op_sel:[0,1,0]
	v_pk_fma_f32 v[104:105], v[116:117], v[118:119], v[104:105] op_sel_hi:[1,0,1]
	v_cvt_scalef32_pk_f32_fp4 v[116:117], v2, 1.0 op_sel:[1,1,0]
	v_pk_fma_f32 v[102:103], v[120:121], v[114:115], v[102:103] op_sel_hi:[1,0,1]
	v_cvt_scalef32_pk_f32_fp4 v[120:121], v10, 1.0 op_sel:[0,1,0]
	v_pk_fma_f32 v[100:101], v[122:123], v[112:113], v[100:101] op_sel_hi:[1,0,1]
	v_pk_fma_f32 v[206:207], v[116:117], v[118:119], v[102:103] op_sel_hi:[1,0,1]
	v_cvt_scalef32_pk_f32_fp4 v[116:117], v6, 1.0 op_sel:[0,1,0]
	v_pk_fma_f32 v[100:101], v[120:121], v[112:113], v[100:101] op_sel:[0,1,0]
	v_cvt_scalef32_pk_f32_fp4 v[120:121], v14, 1.0 op_sel:[1,0,0]
	v_cvt_scalef32_pk_f32_fp4 v[14:15], v14, 1.0
	v_cvt_scalef32_pk_f32_fp4 v[102:103], v2, 1.0 op_sel:[0,1,0]
	v_pk_fma_f32 v[100:101], v[116:117], v[114:115], v[100:101] op_sel_hi:[1,0,1]
	v_cvt_scalef32_pk_f32_fp4 v[116:117], v10, 1.0 op_sel:[1,0,0]
	v_cvt_scalef32_pk_f32_fp4 v[10:11], v10, 1.0
	v_pk_fma_f32 v[14:15], v[14:15], v[112:113], v[96:97] op_sel_hi:[1,0,1]
	v_pk_fma_f32 v[208:209], v[102:103], v[118:119], v[100:101] op_sel_hi:[1,0,1]
	v_cvt_scalef32_pk_f32_fp4 v[102:103], v6, 1.0 op_sel:[1,0,0]
	v_cvt_scalef32_pk_f32_fp4 v[6:7], v6, 1.0
	v_pk_fma_f32 v[10:11], v[10:11], v[112:113], v[14:15] op_sel:[0,1,0]
	v_cvt_scalef32_pk_f32_fp4 v[14:15], v13, 1.0 op_sel:[1,1,0]
	v_cvt_scalef32_pk_f32_fp4 v[100:101], v2, 1.0 op_sel:[1,0,0]
	v_cvt_scalef32_pk_f32_fp4 v[2:3], v2, 1.0
	v_pk_fma_f32 v[6:7], v[6:7], v[114:115], v[10:11] op_sel_hi:[1,0,1]
	v_cvt_scalef32_pk_f32_fp4 v[10:11], v9, 1.0 op_sel:[1,1,0]
	v_pk_fma_f32 v[14:15], v[14:15], v[112:113], v[94:95] op_sel_hi:[1,0,1]
	v_pk_fma_f32 v[212:213], v[2:3], v[118:119], v[6:7] op_sel_hi:[1,0,1]
	v_cvt_scalef32_pk_f32_fp4 v[6:7], v5, 1.0 op_sel:[1,1,0]
	v_pk_fma_f32 v[10:11], v[10:11], v[112:113], v[14:15] op_sel:[0,1,0]
	v_cvt_scalef32_pk_f32_fp4 v[14:15], v13, 1.0 op_sel:[0,1,0]
	v_cvt_scalef32_pk_f32_fp4 v[2:3], v1, 1.0 op_sel:[1,1,0]
	v_pk_fma_f32 v[6:7], v[6:7], v[114:115], v[10:11] op_sel_hi:[1,0,1]
	v_cvt_scalef32_pk_f32_fp4 v[10:11], v9, 1.0 op_sel:[0,1,0]
	v_pk_fma_f32 v[14:15], v[14:15], v[112:113], v[92:93] op_sel_hi:[1,0,1]
	v_pk_fma_f32 v[214:215], v[2:3], v[118:119], v[6:7] op_sel_hi:[1,0,1]
	v_cvt_scalef32_pk_f32_fp4 v[6:7], v5, 1.0 op_sel:[0,1,0]
	v_pk_fma_f32 v[10:11], v[10:11], v[112:113], v[14:15] op_sel:[0,1,0]
	v_cvt_scalef32_pk_f32_fp4 v[14:15], v13, 1.0 op_sel:[1,0,0]
	v_cvt_scalef32_pk_f32_fp4 v[2:3], v1, 1.0 op_sel:[0,1,0]
	v_pk_fma_f32 v[6:7], v[6:7], v[114:115], v[10:11] op_sel_hi:[1,0,1]
	v_cvt_scalef32_pk_f32_fp4 v[10:11], v9, 1.0 op_sel:[1,0,0]
	v_pk_fma_f32 v[14:15], v[14:15], v[112:113], v[90:91] op_sel_hi:[1,0,1]
	v_pk_fma_f32 v[216:217], v[2:3], v[118:119], v[6:7] op_sel_hi:[1,0,1]
	v_cvt_scalef32_pk_f32_fp4 v[6:7], v5, 1.0 op_sel:[1,0,0]
	v_pk_fma_f32 v[10:11], v[10:11], v[112:113], v[14:15] op_sel:[0,1,0]
	v_cvt_scalef32_pk_f32_fp4 v[14:15], v13, 1.0
	v_cvt_scalef32_pk_f32_fp4 v[2:3], v1, 1.0 op_sel:[1,0,0]
	v_pk_fma_f32 v[6:7], v[6:7], v[114:115], v[10:11] op_sel_hi:[1,0,1]
	v_cvt_scalef32_pk_f32_fp4 v[10:11], v9, 1.0
	v_pk_fma_f32 v[14:15], v[14:15], v[112:113], v[88:89] op_sel_hi:[1,0,1]
	v_pk_fma_f32 v[218:219], v[2:3], v[118:119], v[6:7] op_sel_hi:[1,0,1]
	v_cvt_scalef32_pk_f32_fp4 v[6:7], v5, 1.0
	v_pk_fma_f32 v[10:11], v[10:11], v[112:113], v[14:15] op_sel:[0,1,0]
	v_cvt_scalef32_pk_f32_fp4 v[14:15], v12, 1.0 op_sel:[1,1,0]
	v_cvt_scalef32_pk_f32_fp4 v[2:3], v1, 1.0
	v_pk_fma_f32 v[6:7], v[6:7], v[114:115], v[10:11] op_sel_hi:[1,0,1]
	v_cvt_scalef32_pk_f32_fp4 v[10:11], v8, 1.0 op_sel:[1,1,0]
	v_pk_fma_f32 v[14:15], v[14:15], v[112:113], v[86:87] op_sel_hi:[1,0,1]
	v_pk_fma_f32 v[220:221], v[2:3], v[118:119], v[6:7] op_sel_hi:[1,0,1]
	v_cvt_scalef32_pk_f32_fp4 v[6:7], v4, 1.0 op_sel:[1,1,0]
	v_pk_fma_f32 v[10:11], v[10:11], v[112:113], v[14:15] op_sel:[0,1,0]
	v_cvt_scalef32_pk_f32_fp4 v[14:15], v12, 1.0 op_sel:[0,1,0]
	v_cvt_scalef32_pk_f32_fp4 v[2:3], v0, 1.0 op_sel:[1,1,0]
	v_pk_fma_f32 v[6:7], v[6:7], v[114:115], v[10:11] op_sel_hi:[1,0,1]
	v_cvt_scalef32_pk_f32_fp4 v[10:11], v8, 1.0 op_sel:[0,1,0]
	v_pk_fma_f32 v[14:15], v[14:15], v[112:113], v[84:85] op_sel_hi:[1,0,1]
	v_pk_fma_f32 v[222:223], v[2:3], v[118:119], v[6:7] op_sel_hi:[1,0,1]
	v_cvt_scalef32_pk_f32_fp4 v[6:7], v4, 1.0 op_sel:[0,1,0]
	v_pk_fma_f32 v[10:11], v[10:11], v[112:113], v[14:15] op_sel:[0,1,0]
	v_cvt_scalef32_pk_f32_fp4 v[14:15], v12, 1.0 op_sel:[1,0,0]
	v_cvt_scalef32_pk_f32_fp4 v[2:3], v0, 1.0 op_sel:[0,1,0]
	v_pk_fma_f32 v[6:7], v[6:7], v[114:115], v[10:11] op_sel_hi:[1,0,1]
	v_cvt_scalef32_pk_f32_fp4 v[10:11], v8, 1.0 op_sel:[1,0,0]
	v_pk_fma_f32 v[14:15], v[14:15], v[112:113], v[82:83] op_sel_hi:[1,0,1]
	v_pk_fma_f32 v[224:225], v[2:3], v[118:119], v[6:7] op_sel_hi:[1,0,1]
	v_cvt_scalef32_pk_f32_fp4 v[6:7], v4, 1.0 op_sel:[1,0,0]
	v_pk_fma_f32 v[10:11], v[10:11], v[112:113], v[14:15] op_sel:[0,1,0]
	v_cvt_scalef32_pk_f32_fp4 v[2:3], v0, 1.0 op_sel:[1,0,0]
	v_pk_fma_f32 v[6:7], v[6:7], v[114:115], v[10:11] op_sel_hi:[1,0,1]
	v_pk_fma_f32 v[98:99], v[120:121], v[112:113], v[98:99] op_sel_hi:[1,0,1]
	v_pk_fma_f32 v[226:227], v[2:3], v[118:119], v[6:7] op_sel_hi:[1,0,1]
	v_cvt_scalef32_pk_f32_fp4 v[6:7], v12, 1.0
	v_cvt_scalef32_pk_f32_fp4 v[2:3], v4, 1.0
	v_cvt_scalef32_pk_f32_fp4 v[4:5], v8, 1.0
	v_pk_fma_f32 v[6:7], v[6:7], v[112:113], v[80:81] op_sel_hi:[1,0,1]
	v_pk_fma_f32 v[98:99], v[116:117], v[112:113], v[98:99] op_sel:[0,1,0]
	v_pk_fma_f32 v[4:5], v[4:5], v[112:113], v[6:7] op_sel:[0,1,0]
	v_pk_fma_f32 v[98:99], v[102:103], v[114:115], v[98:99] op_sel_hi:[1,0,1]
	v_cvt_scalef32_pk_f32_fp4 v[0:1], v0, 1.0
	v_pk_fma_f32 v[2:3], v[2:3], v[114:115], v[4:5] op_sel_hi:[1,0,1]
	v_pk_fma_f32 v[210:211], v[100:101], v[118:119], v[98:99] op_sel_hi:[1,0,1]
	v_pk_fma_f32 v[228:229], v[0:1], v[118:119], v[2:3] op_sel_hi:[1,0,1]
	v_add_u32_e32 v0, s12, v119
	ds_read_b128 v[0:3], v0 offset:5104
	s_mul_i32 s12, s8, s33
	v_add_u32_e32 v4, s12, v172
	v_ashrrev_i32_e32 v6, 11, v4
	v_mul_i32_i24_e32 v6, 0x3000, v6
	v_ashrrev_i32_e32 v7, 31, v6
	v_lshl_add_u64 v[6:7], v[6:7], 2, s[72:73]
	v_lshl_add_u64 v[6:7], v[34:35], 2, v[6:7]
	v_add_co_u32_e32 v198, vcc, s80, v6
	v_ashrrev_i32_e32 v5, 31, v4
	s_nop 0
	v_addc_co_u32_e32 v199, vcc, 0, v7, vcc
	v_lshlrev_b64 v[4:5], 13, v[4:5]
	global_load_dwordx4 v[8:11], v[198:199], off offset:-4096
	v_lshl_add_u64 v[92:93], v[6:7], 0, s[54:55]
	v_lshl_add_u64 v[6:7], v[46:47], 0, v[4:5]
	global_load_dwordx4 v[12:15], v[6:7], off nt
	global_load_dwordx4 v[80:83], v[6:7], off offset:1024 nt
	global_load_dwordx4 v[84:87], v[92:93], off offset:1024
	global_load_dwordx4 v[88:91], v[92:93], off offset:2048
	s_nop 0
	global_load_dwordx4 v[92:95], v[92:93], off offset:3072
	s_nop 0
	global_load_dwordx4 v[96:99], v[6:7], off offset:2048 nt
	global_load_dwordx4 v[100:103], v[6:7], off offset:3072 nt
	global_load_dwordx4 v[112:115], v[198:199], off
	v_add_co_u32_e32 v4, vcc, s63, v6
	v_mov_b32_e32 v230, v228
	s_nop 0
	v_addc_co_u32_e32 v5, vcc, 0, v7, vcc
	global_load_dwordx4 v[116:119], v[4:5], off nt
	global_load_dwordx4 v[120:123], v[4:5], off offset:1024 nt
	global_load_dwordx4 v[124:127], v[198:199], off offset:1024
	global_load_dwordx4 v[128:131], v[198:199], off offset:2048
	global_load_dwordx4 v[132:135], v[4:5], off offset:2048 nt
	global_load_dwordx4 v[194:197], v[4:5], off offset:3072 nt
	s_nop 0
	global_load_dwordx4 v[198:201], v[198:199], off offset:3072
	s_nop 0
	global_load_dwordx4 v[202:205], v[36:37], off
	v_mov_b32_e32 v231, v226
	v_mov_b32_e32 v232, v224
	v_mov_b32_e32 v233, v222
	v_mov_b32_e32 v226, v229
	v_mov_b32_e32 v222, v225
	v_mov_b32_e32 v229, v214
	v_mov_b32_e32 v214, v217
	v_mov_b32_e32 v224, v220
	v_mov_b32_e32 v225, v218
	v_mov_b32_e32 v218, v221
	v_mov_b32_e32 v220, v208
	v_mov_b32_e32 v221, v206
	v_mov_b32_e32 v206, v209
	v_mov_b32_e32 v208, v104
	v_mov_b32_e32 v209, v106
	v_mov_b32_e32 v106, v105
	v_mov_b32_e32 v228, v216
	v_mov_b32_e32 v216, v212
	v_mov_b32_e32 v217, v210
	v_mov_b32_e32 v210, v213
	v_mov_b32_e32 v212, v108
	v_mov_b32_e32 v213, v110
	v_mov_b32_e32 v110, v109
	s_waitcnt vmcnt(15)
	v_pk_fma_f32 v[8:9], v[230:231], v[8:9], v[12:13]
	v_pk_fma_f32 v[10:11], v[232:233], v[10:11], v[14:15]
	s_waitcnt vmcnt(13)
	v_pk_fma_f32 v[14:15], v[222:223], v[86:87], v[82:83]
	s_waitcnt vmcnt(9)
	v_pk_fma_f32 v[86:87], v[214:215], v[94:95], v[102:103]
	v_pk_mul_f32 v[102:103], v[8:9], v[8:9]
	v_pk_mul_f32 v[104:105], v[10:11], v[10:11]
	v_add_f32_e32 v102, v102, v103
	v_pk_fma_f32 v[12:13], v[226:227], v[84:85], v[80:81]
	v_add_f32_e32 v102, v104, v102
	v_pk_fma_f32 v[84:85], v[218:219], v[92:93], v[100:101]
	s_waitcnt vmcnt(1)
	v_pk_fma_f32 v[100:101], v[106:107], v[198:199], v[194:195]
	v_pk_mul_f32 v[106:107], v[12:13], v[12:13]
	v_add_f32_e32 v102, v105, v102
	v_add_f32_e32 v102, v106, v102
	v_pk_mul_f32 v[108:109], v[14:15], v[14:15]
	v_add_f32_e32 v102, v107, v102
	v_pk_fma_f32 v[80:81], v[224:225], v[88:89], v[96:97]
	v_add_f32_e32 v102, v108, v102
	v_pk_fma_f32 v[88:89], v[216:217], v[112:113], v[116:117]
	v_pk_mul_f32 v[112:113], v[80:81], v[80:81]
	v_add_f32_e32 v102, v109, v102
	v_pk_fma_f32 v[82:83], v[228:229], v[90:91], v[98:99]
	v_add_f32_e32 v102, v112, v102
	v_pk_fma_f32 v[90:91], v[220:221], v[114:115], v[118:119]
	v_pk_mul_f32 v[114:115], v[82:83], v[82:83]
	v_add_f32_e32 v102, v113, v102
	v_add_f32_e32 v102, v114, v102
	v_pk_mul_f32 v[116:117], v[84:85], v[84:85]
	v_add_f32_e32 v102, v115, v102
	v_add_f32_e32 v102, v116, v102
	v_pk_mul_f32 v[118:119], v[86:87], v[86:87]
	v_add_f32_e32 v102, v117, v102
	v_add_f32_e32 v102, v118, v102
	v_pk_fma_f32 v[92:93], v[210:211], v[124:125], v[120:121]
	v_pk_mul_f32 v[120:121], v[88:89], v[88:89]
	v_add_f32_e32 v102, v119, v102
	v_add_f32_e32 v102, v120, v102
	v_pk_fma_f32 v[94:95], v[206:207], v[126:127], v[122:123]
	v_pk_mul_f32 v[122:123], v[90:91], v[90:91]
	v_add_f32_e32 v102, v121, v102
	v_add_f32_e32 v102, v122, v102
	v_pk_mul_f32 v[124:125], v[92:93], v[92:93]
	v_add_f32_e32 v102, v123, v102
	v_add_f32_e32 v102, v124, v102
	v_pk_mul_f32 v[126:127], v[94:95], v[94:95]
	v_add_f32_e32 v102, v125, v102
	v_pk_fma_f32 v[96:97], v[208:209], v[128:129], v[132:133]
	v_add_f32_e32 v102, v126, v102
	v_pk_mul_f32 v[128:129], v[96:97], v[96:97]
	v_add_f32_e32 v102, v127, v102
	v_pk_fma_f32 v[98:99], v[212:213], v[130:131], v[134:135]
	v_add_f32_e32 v102, v128, v102
	v_pk_mul_f32 v[130:131], v[98:99], v[98:99]
	v_add_f32_e32 v102, v129, v102
	v_add_f32_e32 v102, v130, v102
	v_pk_mul_f32 v[132:133], v[100:101], v[100:101]
	v_add_f32_e32 v102, v131, v102
	v_pk_fma_f32 v[110:111], v[110:111], v[200:201], v[196:197]
	v_add_f32_e32 v102, v132, v102
	v_pk_mul_f32 v[134:135], v[110:111], v[110:111]
	v_add_f32_e32 v102, v133, v102
	v_add_f32_e32 v102, v134, v102
	v_add_f32_e32 v102, v135, v102
	global_load_dwordx4 v[244:247], v[36:37], off offset:1024
	global_load_dwordx4 v[248:251], v[36:37], off offset:2048
	global_load_dwordx4 v[252:255], v[36:37], off offset:3072
	s_nop 1
	v_add_f32_dpp v102, v102, v102 quad_perm:[1,0,3,2] row_mask:0xf bank_mask:0xf bound_ctrl:1
	s_nop 1
	v_add_f32_dpp v102, v102, v102 quad_perm:[2,3,0,1] row_mask:0xf bank_mask:0xf bound_ctrl:1
	s_nop 1
	v_add_f32_dpp v102, v102, v102 row_half_mirror row_mask:0xf bank_mask:0xf bound_ctrl:1
	s_nop 1
	v_add_f32_dpp v102, v102, v102 row_mirror row_mask:0xf bank_mask:0xf bound_ctrl:1
	v_mov_b32_e32 v103, v102
	s_nop 1
	v_permlane16_swap_b32_e32 v102, v103
	v_add_f32_e32 v102, v102, v103
	v_mov_b32_e32 v103, v102
	s_nop 1
	v_permlane32_swap_b32_e32 v102, v103
	v_add_f32_e32 v102, v102, v103
	v_fmamk_f32 v102, v102, 0x3a000000, v184
	v_mul_f32_e32 v103, 0x4b800000, v102
	v_cmp_gt_f32_e32 vcc, s64, v102
	s_nop 1
	v_cndmask_b32_e32 v102, v102, v103, vcc
	v_rsq_f32_e32 v102, v102
	s_nop 0
	v_mul_f32_e32 v103, 0x45800000, v102
	v_cndmask_b32_e32 v102, v102, v103, vcc
	v_pk_mul_f32 v[8:9], v[8:9], v[102:103] op_sel_hi:[1,0]
	v_pk_mul_f32 v[10:11], v[10:11], v[102:103] op_sel_hi:[1,0]
	s_waitcnt vmcnt(3)
	v_pk_mul_f32 v[8:9], v[202:203], v[8:9]
	v_pk_mul_f32 v[10:11], v[204:205], v[10:11]
	global_store_dwordx4 v[6:7], v[8:11], off nt
	v_pk_mul_f32 v[14:15], v[14:15], v[102:103] op_sel_hi:[1,0]
	v_pk_mul_f32 v[12:13], v[12:13], v[102:103] op_sel_hi:[1,0]
	s_andn2_b64 vcc, exec, s[6:7]
	s_waitcnt vmcnt(3)
	v_pk_mul_f32 v[244:245], v[244:245], v[12:13]
	v_pk_mul_f32 v[246:247], v[246:247], v[14:15]
	global_store_dwordx4 v[6:7], v[244:247], off offset:1024 nt
	s_nop 0
	global_load_dwordx4 v[244:247], v[38:39], off
	v_pk_mul_f32 v[12:13], v[82:83], v[102:103] op_sel_hi:[1,0]
	v_pk_mul_f32 v[14:15], v[80:81], v[102:103] op_sel_hi:[1,0]
	s_waitcnt vmcnt(4)
	v_pk_mul_f32 v[250:251], v[250:251], v[12:13]
	v_pk_mul_f32 v[248:249], v[248:249], v[14:15]
	global_store_dwordx4 v[6:7], v[248:251], off offset:2048 nt
	s_nop 0
	global_load_dwordx4 v[248:251], v[40:41], off
	v_pk_mul_f32 v[12:13], v[86:87], v[102:103] op_sel_hi:[1,0]
	v_pk_mul_f32 v[14:15], v[84:85], v[102:103] op_sel_hi:[1,0]
	s_waitcnt vmcnt(5)
	v_pk_mul_f32 v[254:255], v[254:255], v[12:13]
	v_pk_mul_f32 v[252:253], v[252:253], v[14:15]
	global_store_dwordx4 v[6:7], v[252:255], off offset:3072 nt
	s_nop 0
	global_load_dwordx4 v[252:255], v[42:43], off
	v_pk_mul_f32 v[12:13], v[88:89], v[102:103] op_sel_hi:[1,0]
	v_pk_mul_f32 v[10:11], v[90:91], v[102:103] op_sel_hi:[1,0]
	s_waitcnt vmcnt(4)
	v_pk_mul_f32 v[244:245], v[244:245], v[12:13]
	v_pk_mul_f32 v[246:247], v[246:247], v[10:11]
	global_store_dwordx4 v[4:5], v[244:247], off nt
	s_nop 0
	global_load_dwordx4 v[244:247], v[44:45], off
	v_pk_mul_f32 v[10:11], v[94:95], v[102:103] op_sel_hi:[1,0]
	v_pk_mul_f32 v[12:13], v[92:93], v[102:103] op_sel_hi:[1,0]
	s_waitcnt vmcnt(4)
	v_pk_mul_f32 v[250:251], v[10:11], v[250:251]
	v_pk_mul_f32 v[248:249], v[12:13], v[248:249]
	global_store_dwordx4 v[4:5], v[248:251], off offset:1024 nt
	v_pk_mul_f32 v[10:11], v[98:99], v[102:103] op_sel_hi:[1,0]
	v_pk_mul_f32 v[12:13], v[96:97], v[102:103] op_sel_hi:[1,0]
	s_waitcnt vmcnt(3)
	v_pk_mul_f32 v[254:255], v[10:11], v[254:255]
	v_pk_mul_f32 v[252:253], v[12:13], v[252:253]
	global_store_dwordx4 v[4:5], v[252:255], off offset:2048 nt
	v_pk_mul_f32 v[10:11], v[110:111], v[102:103] op_sel_hi:[1,0]
	v_pk_mul_f32 v[12:13], v[100:101], v[102:103] op_sel_hi:[1,0]
	s_waitcnt vmcnt(2)
	v_pk_mul_f32 v[246:247], v[10:11], v[246:247]
	v_pk_mul_f32 v[244:245], v[12:13], v[244:245]
	global_store_dwordx4 v[4:5], v[244:247], off offset:3072 nt
	s_cbranch_vccnz .LBB0_806
	v_cvt_scalef32_pk_f32_fp4 v[10:11], v19, 1.0 op_sel:[1,1,0]
	v_cvt_scalef32_pk_f32_fp4 v[8:9], v23, 1.0 op_sel:[1,1,0]
	s_waitcnt lgkmcnt(0)
	v_pk_fma_f32 v[10:11], v[10:11], v[0:1], v[78:79] op_sel_hi:[1,0,1]
	v_cvt_scalef32_pk_f32_fp4 v[12:13], v19, 1.0 op_sel:[0,1,0]
	v_cvt_scalef32_pk_f32_fp4 v[6:7], v27, 1.0 op_sel:[1,1,0]
	v_pk_fma_f32 v[8:9], v[8:9], v[0:1], v[10:11] op_sel:[0,1,0]
	v_cvt_scalef32_pk_f32_fp4 v[10:11], v23, 1.0 op_sel:[0,1,0]
	v_pk_fma_f32 v[12:13], v[12:13], v[0:1], v[76:77] op_sel_hi:[1,0,1]
	v_cvt_scalef32_pk_f32_fp4 v[14:15], v19, 1.0 op_sel:[1,0,0]
	v_cvt_scalef32_pk_f32_fp4 v[4:5], v31, 1.0 op_sel:[1,1,0]
	v_mov_b32_e32 v124, v3
	v_pk_fma_f32 v[6:7], v[6:7], v[2:3], v[8:9] op_sel_hi:[1,0,1]
	v_cvt_scalef32_pk_f32_fp4 v[8:9], v27, 1.0 op_sel:[0,1,0]
	v_pk_fma_f32 v[10:11], v[10:11], v[0:1], v[12:13] op_sel:[0,1,0]
	v_cvt_scalef32_pk_f32_fp4 v[12:13], v23, 1.0 op_sel:[1,0,0]
	v_pk_fma_f32 v[14:15], v[14:15], v[0:1], v[74:75] op_sel_hi:[1,0,1]
	v_cvt_scalef32_pk_f32_fp4 v[74:75], v19, 1.0
	v_pk_fma_f32 v[4:5], v[4:5], v[124:125], v[6:7] op_sel_hi:[1,0,1]
	v_cvt_scalef32_pk_f32_fp4 v[6:7], v31, 1.0 op_sel:[0,1,0]
	v_pk_fma_f32 v[8:9], v[8:9], v[2:3], v[10:11] op_sel_hi:[1,0,1]
	v_cvt_scalef32_pk_f32_fp4 v[10:11], v27, 1.0 op_sel:[1,0,0]
	v_pk_fma_f32 v[12:13], v[12:13], v[0:1], v[14:15] op_sel:[0,1,0]
	v_cvt_scalef32_pk_f32_fp4 v[14:15], v23, 1.0
	v_pk_fma_f32 v[72:73], v[74:75], v[0:1], v[72:73] op_sel_hi:[1,0,1]
	v_cvt_scalef32_pk_f32_fp4 v[74:75], v18, 1.0 op_sel:[1,1,0]
	v_pk_fma_f32 v[6:7], v[6:7], v[124:125], v[8:9] op_sel_hi:[1,0,1]
	v_cvt_scalef32_pk_f32_fp4 v[8:9], v31, 1.0 op_sel:[1,0,0]
	v_pk_fma_f32 v[10:11], v[10:11], v[2:3], v[12:13] op_sel_hi:[1,0,1]
	v_cvt_scalef32_pk_f32_fp4 v[12:13], v27, 1.0
	v_pk_fma_f32 v[14:15], v[14:15], v[0:1], v[72:73] op_sel:[0,1,0]
	v_cvt_scalef32_pk_f32_fp4 v[72:73], v22, 1.0 op_sel:[1,1,0]
	v_pk_fma_f32 v[70:71], v[74:75], v[0:1], v[70:71] op_sel_hi:[1,0,1]
	v_pk_fma_f32 v[10:11], v[8:9], v[124:125], v[10:11] op_sel_hi:[1,0,1]
	v_cvt_scalef32_pk_f32_fp4 v[8:9], v31, 1.0
	v_pk_fma_f32 v[12:13], v[12:13], v[2:3], v[14:15] op_sel_hi:[1,0,1]
	v_cvt_scalef32_pk_f32_fp4 v[14:15], v26, 1.0 op_sel:[1,1,0]
	v_pk_fma_f32 v[70:71], v[72:73], v[0:1], v[70:71] op_sel:[0,1,0]
	v_cvt_scalef32_pk_f32_fp4 v[74:75], v18, 1.0 op_sel:[0,1,0]
	v_pk_fma_f32 v[12:13], v[8:9], v[124:125], v[12:13] op_sel_hi:[1,0,1]
	v_cvt_scalef32_pk_f32_fp4 v[8:9], v30, 1.0 op_sel:[1,1,0]
	v_pk_fma_f32 v[14:15], v[14:15], v[2:3], v[70:71] op_sel_hi:[1,0,1]
	v_cvt_scalef32_pk_f32_fp4 v[72:73], v22, 1.0 op_sel:[0,1,0]
	v_pk_fma_f32 v[68:69], v[74:75], v[0:1], v[68:69] op_sel_hi:[1,0,1]
	v_pk_fma_f32 v[70:71], v[8:9], v[124:125], v[14:15] op_sel_hi:[1,0,1]
	v_cvt_scalef32_pk_f32_fp4 v[14:15], v26, 1.0 op_sel:[0,1,0]
	v_pk_fma_f32 v[68:69], v[72:73], v[0:1], v[68:69] op_sel:[0,1,0]
	v_cvt_scalef32_pk_f32_fp4 v[74:75], v18, 1.0 op_sel:[1,0,0]
	v_cvt_scalef32_pk_f32_fp4 v[8:9], v30, 1.0 op_sel:[0,1,0]
	v_pk_fma_f32 v[14:15], v[14:15], v[2:3], v[68:69] op_sel_hi:[1,0,1]
	v_cvt_scalef32_pk_f32_fp4 v[72:73], v22, 1.0 op_sel:[1,0,0]
	v_pk_fma_f32 v[66:67], v[74:75], v[0:1], v[66:67] op_sel_hi:[1,0,1]
	v_pk_fma_f32 v[68:69], v[8:9], v[124:125], v[14:15] op_sel_hi:[1,0,1]
	v_cvt_scalef32_pk_f32_fp4 v[14:15], v26, 1.0 op_sel:[1,0,0]
	v_pk_fma_f32 v[66:67], v[72:73], v[0:1], v[66:67] op_sel:[0,1,0]
	v_cvt_scalef32_pk_f32_fp4 v[18:19], v18, 1.0
	v_cvt_scalef32_pk_f32_fp4 v[8:9], v30, 1.0 op_sel:[1,0,0]
	v_pk_fma_f32 v[14:15], v[14:15], v[2:3], v[66:67] op_sel_hi:[1,0,1]
	v_cvt_scalef32_pk_f32_fp4 v[22:23], v22, 1.0
	v_pk_fma_f32 v[18:19], v[18:19], v[0:1], v[64:65] op_sel_hi:[1,0,1]
	v_pk_fma_f32 v[66:67], v[8:9], v[124:125], v[14:15] op_sel_hi:[1,0,1]
	v_cvt_scalef32_pk_f32_fp4 v[14:15], v26, 1.0
	v_pk_fma_f32 v[18:19], v[22:23], v[0:1], v[18:19] op_sel:[0,1,0]
	v_cvt_scalef32_pk_f32_fp4 v[26:27], v17, 1.0 op_sel:[1,1,0]
	v_cvt_scalef32_pk_f32_fp4 v[8:9], v30, 1.0
	v_pk_fma_f32 v[14:15], v[14:15], v[2:3], v[18:19] op_sel_hi:[1,0,1]
	v_cvt_scalef32_pk_f32_fp4 v[22:23], v21, 1.0 op_sel:[1,1,0]
	v_pk_fma_f32 v[26:27], v[26:27], v[0:1], v[62:63] op_sel_hi:[1,0,1]
	v_pk_fma_f32 v[18:19], v[8:9], v[124:125], v[14:15] op_sel_hi:[1,0,1]
	v_cvt_scalef32_pk_f32_fp4 v[14:15], v25, 1.0 op_sel:[1,1,0]
	v_pk_fma_f32 v[22:23], v[22:23], v[0:1], v[26:27] op_sel:[0,1,0]
	v_cvt_scalef32_pk_f32_fp4 v[8:9], v29, 1.0 op_sel:[1,1,0]
	v_pk_fma_f32 v[14:15], v[14:15], v[2:3], v[22:23] op_sel_hi:[1,0,1]
	s_mul_i32 s11, s11, s33
	v_pk_fma_f32 v[22:23], v[8:9], v[124:125], v[14:15] op_sel_hi:[1,0,1]
	v_add_u32_e32 v8, s11, v172
	v_ashrrev_i32_e32 v3, 11, v8
	v_mul_i32_i24_e32 v14, 0x3000, v3
	v_ashrrev_i32_e32 v15, 31, v14
	v_lshl_add_u64 v[14:15], v[14:15], 2, s[72:73]
	v_lshl_add_u64 v[26:27], v[34:35], 2, v[14:15]
	v_ashrrev_i32_e32 v9, 31, v8
	v_add_co_u32_e32 v30, vcc, s80, v26
	v_lshlrev_b64 v[8:9], 13, v[8:9]
	s_nop 0
	v_addc_co_u32_e32 v31, vcc, 0, v27, vcc
	global_load_dwordx4 v[62:65], v[30:31], off offset:-4096
	v_lshl_add_u64 v[14:15], v[46:47], 0, v[8:9]
	global_load_dwordx4 v[72:75], v[14:15], off nt
	v_lshl_add_u64 v[26:27], v[26:27], 0, s[54:55]
	v_cvt_scalef32_pk_f32_fp4 v[80:81], v17, 1.0 op_sel:[0,1,0]
	global_load_dwordx4 v[76:79], v[26:27], off offset:1024
	v_pk_fma_f32 v[60:61], v[80:81], v[0:1], v[60:61] op_sel_hi:[1,0,1]
	global_load_dwordx4 v[80:83], v[14:15], off offset:1024 nt
	v_cvt_scalef32_pk_f32_fp4 v[86:87], v21, 1.0 op_sel:[0,1,0]
	v_cvt_scalef32_pk_f32_fp4 v[84:85], v25, 1.0 op_sel:[0,1,0]
	v_pk_fma_f32 v[60:61], v[86:87], v[0:1], v[60:61] op_sel:[0,1,0]
	v_cvt_scalef32_pk_f32_fp4 v[94:95], v17, 1.0 op_sel:[1,0,0]
	v_pk_fma_f32 v[60:61], v[84:85], v[2:3], v[60:61] op_sel_hi:[1,0,1]
	global_load_dwordx4 v[84:87], v[26:27], off offset:2048
	global_load_dwordx4 v[88:91], v[14:15], off offset:2048 nt
	v_cvt_scalef32_pk_f32_fp4 v[8:9], v29, 1.0 op_sel:[0,1,0]
	v_cvt_scalef32_pk_f32_fp4 v[92:93], v21, 1.0 op_sel:[1,0,0]
	v_pk_fma_f32 v[58:59], v[94:95], v[0:1], v[58:59] op_sel_hi:[1,0,1]
	v_pk_fma_f32 v[126:127], v[8:9], v[124:125], v[60:61] op_sel_hi:[1,0,1]
	v_cvt_scalef32_pk_f32_fp4 v[60:61], v25, 1.0 op_sel:[1,0,0]
	v_pk_fma_f32 v[58:59], v[92:93], v[0:1], v[58:59] op_sel:[0,1,0]
	v_cvt_scalef32_pk_f32_fp4 v[8:9], v29, 1.0 op_sel:[1,0,0]
	v_pk_fma_f32 v[96:97], v[60:61], v[2:3], v[58:59] op_sel_hi:[1,0,1]
	global_load_dwordx4 v[58:61], v[26:27], off offset:3072
	global_load_dwordx4 v[92:95], v[14:15], off offset:3072 nt
	v_pk_fma_f32 v[26:27], v[8:9], v[124:125], v[96:97] op_sel_hi:[1,0,1]
	v_add_co_u32_e32 v8, vcc, s63, v14
	global_load_dwordx4 v[96:99], v[30:31], off
	s_nop 0
	v_addc_co_u32_e32 v9, vcc, 0, v15, vcc
	global_load_dwordx4 v[100:103], v[8:9], off nt
	v_cvt_scalef32_pk_f32_fp4 v[104:105], v17, 1.0
	v_pk_fma_f32 v[56:57], v[104:105], v[0:1], v[56:57] op_sel_hi:[1,0,1]
	global_load_dwordx4 v[104:107], v[30:31], off offset:1024
	global_load_dwordx4 v[108:111], v[8:9], off offset:1024 nt
	v_cvt_scalef32_pk_f32_fp4 v[116:117], v21, 1.0
	v_cvt_scalef32_pk_f32_fp4 v[114:115], v25, 1.0
	v_pk_fma_f32 v[56:57], v[116:117], v[0:1], v[56:57] op_sel:[0,1,0]
	v_cvt_scalef32_pk_f32_fp4 v[112:113], v29, 1.0
	v_pk_fma_f32 v[56:57], v[114:115], v[2:3], v[56:57] op_sel_hi:[1,0,1]
	v_cvt_scalef32_pk_f32_fp4 v[122:123], v16, 1.0 op_sel:[1,1,0]
	v_pk_fma_f32 v[128:129], v[112:113], v[124:125], v[56:57] op_sel_hi:[1,0,1]
	global_load_dwordx4 v[112:115], v[30:31], off offset:2048
	global_load_dwordx4 v[116:119], v[8:9], off offset:2048 nt
	v_cvt_scalef32_pk_f32_fp4 v[120:121], v20, 1.0 op_sel:[1,1,0]
	v_pk_fma_f32 v[54:55], v[122:123], v[0:1], v[54:55] op_sel_hi:[1,0,1]
	v_cvt_scalef32_pk_f32_fp4 v[56:57], v24, 1.0 op_sel:[1,1,0]
	v_pk_fma_f32 v[54:55], v[120:121], v[0:1], v[54:55] op_sel:[0,1,0]
	v_cvt_scalef32_pk_f32_fp4 v[194:195], v16, 1.0 op_sel:[0,1,0]
	v_pk_fma_f32 v[132:133], v[56:57], v[2:3], v[54:55] op_sel_hi:[1,0,1]
	global_load_dwordx4 v[54:57], v[30:31], off offset:3072
	global_load_dwordx4 v[120:123], v[8:9], off offset:3072 nt
	v_cvt_scalef32_pk_f32_fp4 v[130:131], v28, 1.0 op_sel:[1,1,0]
	v_cvt_scalef32_pk_f32_fp4 v[134:135], v20, 1.0 op_sel:[0,1,0]
	v_pk_fma_f32 v[52:53], v[194:195], v[0:1], v[52:53] op_sel_hi:[1,0,1]
	v_cvt_scalef32_pk_f32_fp4 v[194:195], v16, 1.0 op_sel:[1,0,0]
	v_cvt_scalef32_pk_f32_fp4 v[16:17], v16, 1.0
	v_pk_fma_f32 v[30:31], v[130:131], v[124:125], v[132:133] op_sel_hi:[1,0,1]
	v_cvt_scalef32_pk_f32_fp4 v[132:133], v24, 1.0 op_sel:[0,1,0]
	v_pk_fma_f32 v[52:53], v[134:135], v[0:1], v[52:53] op_sel:[0,1,0]
	v_cvt_scalef32_pk_f32_fp4 v[134:135], v20, 1.0 op_sel:[1,0,0]
	v_pk_fma_f32 v[50:51], v[194:195], v[0:1], v[50:51] op_sel_hi:[1,0,1]
	v_cvt_scalef32_pk_f32_fp4 v[20:21], v20, 1.0
	v_pk_fma_f32 v[16:17], v[16:17], v[0:1], v[48:49] op_sel_hi:[1,0,1]
	v_cvt_scalef32_pk_f32_fp4 v[130:131], v28, 1.0 op_sel:[0,1,0]
	v_pk_fma_f32 v[52:53], v[132:133], v[2:3], v[52:53] op_sel_hi:[1,0,1]
	v_cvt_scalef32_pk_f32_fp4 v[132:133], v24, 1.0 op_sel:[1,0,0]
	v_pk_fma_f32 v[50:51], v[134:135], v[0:1], v[50:51] op_sel:[0,1,0]
	v_cvt_scalef32_pk_f32_fp4 v[24:25], v24, 1.0
	v_pk_fma_f32 v[0:1], v[20:21], v[0:1], v[16:17] op_sel:[0,1,0]
	v_pk_fma_f32 v[52:53], v[130:131], v[124:125], v[52:53] op_sel_hi:[1,0,1]
	v_cvt_scalef32_pk_f32_fp4 v[130:131], v28, 1.0 op_sel:[1,0,0]
	v_cvt_scalef32_pk_f32_fp4 v[28:29], v28, 1.0
	v_pk_fma_f32 v[0:1], v[24:25], v[2:3], v[0:1] op_sel_hi:[1,0,1]
	v_pk_fma_f32 v[50:51], v[132:133], v[2:3], v[50:51] op_sel_hi:[1,0,1]
	v_pk_fma_f32 v[16:17], v[28:29], v[124:125], v[0:1] op_sel_hi:[1,0,1]
	global_load_dwordx4 v[0:3], v[36:37], off
	v_pk_fma_f32 v[50:51], v[130:131], v[124:125], v[50:51] op_sel_hi:[1,0,1]
	v_mov_b32_e32 v28, v52
	v_mov_b32_e32 v21, v50
	v_mov_b32_e32 v29, v30
	v_mov_b32_e32 v30, v53
	s_waitcnt vmcnt(16)
	v_mov_b32_e32 v20, v62
	v_mov_b32_e32 v62, v16
	s_waitcnt vmcnt(15)
	v_pk_fma_f32 v[20:21], v[20:21], v[62:63], v[72:73]
	v_pk_fma_f32 v[28:29], v[28:29], v[64:65], v[74:75]
	v_pk_mul_f32 v[24:25], v[20:21], v[20:21]
	v_pk_mul_f32 v[48:49], v[28:29], v[28:29]
	s_waitcnt vmcnt(14)
	v_mov_b32_e32 v50, v76
	v_mov_b32_e32 v76, v17
	v_add_f32_e32 v24, v25, v24
	s_waitcnt vmcnt(13)
	v_pk_fma_f32 v[16:17], v[50:51], v[76:77], v[80:81]
	v_add_f32_e32 v24, v48, v24
	v_pk_mul_f32 v[50:51], v[16:17], v[16:17]
	v_add_f32_e32 v24, v49, v24
	v_pk_fma_f32 v[30:31], v[30:31], v[78:79], v[82:83]
	v_add_f32_e32 v24, v50, v24
	v_pk_mul_f32 v[52:53], v[30:31], v[30:31]
	v_mov_b32_e32 v62, v128
	v_mov_b32_e32 v63, v26
	v_add_f32_e32 v24, v51, v24
	s_waitcnt vmcnt(11)
	v_pk_fma_f32 v[62:63], v[62:63], v[84:85], v[88:89]
	v_add_f32_e32 v24, v52, v24
	v_pk_mul_f32 v[64:65], v[62:63], v[62:63]
	v_mov_b32_e32 v72, v126
	v_mov_b32_e32 v73, v22
	v_add_f32_e32 v24, v53, v24
	v_pk_fma_f32 v[72:73], v[72:73], v[86:87], v[90:91]
	v_add_f32_e32 v24, v64, v24
	v_pk_mul_f32 v[74:75], v[72:73], v[72:73]
	v_mov_b32_e32 v26, v129
	v_add_f32_e32 v24, v65, v24
	s_waitcnt vmcnt(9)
	v_pk_fma_f32 v[26:27], v[26:27], v[58:59], v[92:93]
	v_add_f32_e32 v24, v74, v24
	v_pk_mul_f32 v[58:59], v[26:27], v[26:27]
	v_mov_b32_e32 v22, v127
	v_add_f32_e32 v24, v75, v24
	v_pk_fma_f32 v[22:23], v[22:23], v[60:61], v[94:95]
	v_add_f32_e32 v24, v58, v24
	v_pk_mul_f32 v[60:61], v[22:23], v[22:23]
	v_mov_b32_e32 v76, v18
	v_mov_b32_e32 v77, v66
	v_add_f32_e32 v24, v59, v24
	s_waitcnt vmcnt(7)
	v_pk_fma_f32 v[76:77], v[76:77], v[96:97], v[100:101]
	v_add_f32_e32 v24, v60, v24
	v_pk_mul_f32 v[78:79], v[76:77], v[76:77]
	v_mov_b32_e32 v80, v68
	v_mov_b32_e32 v81, v70
	v_add_f32_e32 v24, v61, v24
	v_pk_fma_f32 v[80:81], v[80:81], v[98:99], v[102:103]
	v_add_f32_e32 v24, v78, v24
	v_pk_mul_f32 v[82:83], v[80:81], v[80:81]
	v_mov_b32_e32 v66, v19
	v_add_f32_e32 v24, v79, v24
	s_waitcnt vmcnt(5)
	v_pk_fma_f32 v[18:19], v[66:67], v[104:105], v[108:109]
	v_add_f32_e32 v24, v82, v24
	v_pk_mul_f32 v[66:67], v[18:19], v[18:19]
	v_mov_b32_e32 v70, v69
	v_add_f32_e32 v24, v83, v24
	v_pk_fma_f32 v[68:69], v[70:71], v[106:107], v[110:111]
	v_add_f32_e32 v24, v66, v24
	v_pk_mul_f32 v[70:71], v[68:69], v[68:69]
	v_mov_b32_e32 v84, v12
	v_mov_b32_e32 v85, v10
	v_add_f32_e32 v24, v67, v24
	s_waitcnt vmcnt(3)
	v_pk_fma_f32 v[84:85], v[84:85], v[112:113], v[116:117]
	v_add_f32_e32 v24, v70, v24
	v_pk_mul_f32 v[86:87], v[84:85], v[84:85]
	v_mov_b32_e32 v88, v6
	v_mov_b32_e32 v89, v4
	v_add_f32_e32 v24, v71, v24
	v_pk_fma_f32 v[88:89], v[88:89], v[114:115], v[118:119]
	v_add_f32_e32 v24, v86, v24
	v_pk_mul_f32 v[90:91], v[88:89], v[88:89]
	v_mov_b32_e32 v10, v13
	v_add_f32_e32 v24, v87, v24
	s_waitcnt vmcnt(1)
	v_pk_fma_f32 v[10:11], v[10:11], v[54:55], v[120:121]
	v_add_f32_e32 v24, v90, v24
	v_pk_mul_f32 v[12:13], v[10:11], v[10:11]
	v_mov_b32_e32 v4, v7
	v_add_f32_e32 v24, v91, v24
	v_pk_fma_f32 v[4:5], v[4:5], v[56:57], v[122:123]
	v_add_f32_e32 v12, v12, v24
	v_pk_mul_f32 v[6:7], v[4:5], v[4:5]
	v_add_f32_e32 v12, v13, v12
	v_add_f32_e32 v6, v6, v12
	v_add_f32_e32 v6, v7, v6
	global_load_dwordx4 v[92:95], v[36:37], off offset:1024
	global_load_dwordx4 v[96:99], v[36:37], off offset:2048
	global_load_dwordx4 v[100:103], v[36:37], off offset:3072
	global_load_dwordx4 v[104:107], v[38:39], off
	global_load_dwordx4 v[108:111], v[40:41], off
	global_load_dwordx4 v[112:115], v[42:43], off
	global_load_dwordx4 v[116:119], v[44:45], off
	s_nop 1
	v_add_f32_dpp v6, v6, v6 quad_perm:[1,0,3,2] row_mask:0xf bank_mask:0xf bound_ctrl:1
	s_nop 1
	v_add_f32_dpp v6, v6, v6 quad_perm:[2,3,0,1] row_mask:0xf bank_mask:0xf bound_ctrl:1
	s_nop 1
	v_add_f32_dpp v6, v6, v6 row_half_mirror row_mask:0xf bank_mask:0xf bound_ctrl:1
	s_nop 1
	v_add_f32_dpp v6, v6, v6 row_mirror row_mask:0xf bank_mask:0xf bound_ctrl:1
	v_mov_b32_e32 v7, v6
	s_nop 1
	v_permlane16_swap_b32_e32 v6, v7
	v_add_f32_e32 v6, v6, v7
	v_mov_b32_e32 v7, v6
	s_nop 1
	v_permlane32_swap_b32_e32 v6, v7
	v_add_f32_e32 v6, v6, v7
	v_fmamk_f32 v6, v6, 0x3a000000, v184
	v_mul_f32_e32 v7, 0x4b800000, v6
	v_cmp_gt_f32_e32 vcc, s64, v6
	s_nop 1
	v_cndmask_b32_e32 v6, v6, v7, vcc
	v_rsq_f32_e32 v6, v6
	s_nop 0
	v_mul_f32_e32 v7, 0x45800000, v6
	v_cndmask_b32_e32 v6, v6, v7, vcc
	v_pk_mul_f32 v[12:13], v[20:21], v[6:7] op_sel_hi:[1,0]
	v_pk_mul_f32 v[20:21], v[28:29], v[6:7] op_sel_hi:[1,0]
	s_waitcnt vmcnt(7)
	v_pk_mul_f32 v[0:1], v[0:1], v[12:13]
	v_pk_mul_f32 v[2:3], v[2:3], v[20:21]
	global_store_dwordx4 v[14:15], v[0:3], off nt
	v_pk_mul_f32 v[12:13], v[30:31], v[6:7] op_sel_hi:[1,0]
	v_pk_mul_f32 v[16:17], v[16:17], v[6:7] op_sel_hi:[1,0]
	v_pk_mul_f32 v[4:5], v[4:5], v[6:7] op_sel_hi:[1,0]
	s_waitcnt vmcnt(7)
	v_pk_mul_f32 v[92:93], v[92:93], v[16:17]
	v_pk_mul_f32 v[94:95], v[94:95], v[12:13]
	global_store_dwordx4 v[14:15], v[92:95], off offset:1024 nt
	v_pk_mul_f32 v[12:13], v[72:73], v[6:7] op_sel_hi:[1,0]
	v_pk_mul_f32 v[16:17], v[62:63], v[6:7] op_sel_hi:[1,0]
	s_waitcnt vmcnt(7)
	v_pk_mul_f32 v[98:99], v[98:99], v[12:13]
	v_pk_mul_f32 v[96:97], v[96:97], v[16:17]
	global_store_dwordx4 v[14:15], v[96:99], off offset:2048 nt
	v_pk_mul_f32 v[12:13], v[22:23], v[6:7] op_sel_hi:[1,0]
	v_pk_mul_f32 v[16:17], v[26:27], v[6:7] op_sel_hi:[1,0]
	s_waitcnt vmcnt(7)
	v_pk_mul_f32 v[102:103], v[102:103], v[12:13]
	v_pk_mul_f32 v[100:101], v[100:101], v[16:17]
	global_store_dwordx4 v[14:15], v[100:103], off offset:3072 nt
	v_pk_mul_f32 v[12:13], v[80:81], v[6:7] op_sel_hi:[1,0]
	v_pk_mul_f32 v[14:15], v[76:77], v[6:7] op_sel_hi:[1,0]
	s_waitcnt vmcnt(7)
	v_pk_mul_f32 v[106:107], v[106:107], v[12:13]
	v_pk_mul_f32 v[104:105], v[104:105], v[14:15]
	global_store_dwordx4 v[8:9], v[104:107], off nt
	v_pk_mul_f32 v[12:13], v[68:69], v[6:7] op_sel_hi:[1,0]
	v_pk_mul_f32 v[14:15], v[18:19], v[6:7] op_sel_hi:[1,0]
	s_waitcnt vmcnt(7)
	v_pk_mul_f32 v[110:111], v[12:13], v[110:111]
	v_pk_mul_f32 v[108:109], v[14:15], v[108:109]
	global_store_dwordx4 v[8:9], v[108:111], off offset:1024 nt
	v_pk_mul_f32 v[12:13], v[88:89], v[6:7] op_sel_hi:[1,0]
	v_pk_mul_f32 v[14:15], v[84:85], v[6:7] op_sel_hi:[1,0]
	v_pk_mul_f32 v[6:7], v[10:11], v[6:7] op_sel_hi:[1,0]
	s_waitcnt vmcnt(7)
	v_pk_mul_f32 v[112:113], v[14:15], v[112:113]
	v_pk_mul_f32 v[114:115], v[12:13], v[114:115]
	global_store_dwordx4 v[8:9], v[112:115], off offset:2048 nt
	s_waitcnt vmcnt(7)
	v_pk_mul_f32 v[116:117], v[6:7], v[116:117]
	v_pk_mul_f32 v[118:119], v[4:5], v[118:119]
	global_store_dwordx4 v[8:9], v[116:119], off offset:3072 nt
	s_branch .LBB0_806
